# hyena SEQ item epilogue: 16 gate-row loads issued before the MFMA loop, U reads batched, one uniform store branch per order
# baseline (speedup 1.0000x reference)
; #define LAS __attribute__((address_space(3)))
; #define MFMA16(a, b, c) __builtin_amdgcn_mfma_f32_16x16x32_bf16((a), (b), (c), 0, 0, 0)
; template <int L>
; __device__ NOINL void hyena_item(const LAS Params* lp, int l, int c, LAS unsigned char* lds) {
;     ...
;         if (tid < 64) { const int r = tid >> 3, k = tid & 7; if (k < r) *(LAS bf16_t*)(lds + r * FSB + (2 * L + 8 - 1 - k) * 2) = 0; }
;         __syncthreads();
;         f32x4 acc[NTB];
; #pragma unroll
;         for (int a = 0; a < NTB; ++a) acc[a] = (f32x4){0.f, 0.f, 0.f, 0.f};
; #pragma unroll 1
;         for (int sb = 0; sb < NS; sb += 4) {
;             bf16x8 Bf[4];
; #pragma unroll
;             for (int u = 0; u < 4; ++u) Bf[u] = *(const LAS bf16x8*)(lds + UOFF + fr * USB + (sb + u) * 64 + fq * 16);
;             bf16x8 Af[NTB + 6];
; #pragma unroll
;             for (int k = 0; k < NTB + 6; ++k) Af[k] = *(const LAS bf16x8*)(lds + abase + sb * 64 + k * 32);
; #pragma unroll
;             for (int a = 0; a < NTB; ++a)
; #pragma unroll
;                 for (int u = 0; u < 4; ++u) acc[a] = MFMA16(Af[NTB - 1 - a + 2 * u], Bf[u], acc[a]);
;         }
;         __syncthreads();
;         const bf16_t* gT = hT + ((size_t)((order + 1) * 256 + c) * NB + fr) * L;
; #pragma unroll
;         for (int a = 0; a < NTB; ++a) {
;             const int t = 16 * (w * NTB + a) + 4 * fq;
;             const u32x2 gv = *(const u32x2*)(gT + t);
.LBB0_1255:
	s_or_b64 exec, exec, s[52:53]
	s_xor_b64 s[52:53], s[46:47], -1
	s_and_saveexec_b64 s[54:55], s[50:51]
	ds_write_b16 v129, v1 offset:8206
	s_or_b64 exec, exec, s[54:55]
	v_mov_b32_e32 v68, 0
	s_mov_b32 s3, -4
	s_mov_b32 s4, 0
	v_mov_b32_e32 v69, v68
	v_mov_b32_e32 v70, v68
	v_mov_b32_e32 v71, v68
	v_mov_b32_e32 v64, v68
	v_mov_b32_e32 v65, v68
	v_mov_b32_e32 v66, v68
	v_mov_b32_e32 v67, v68
	v_mov_b32_e32 v60, v68
	v_mov_b32_e32 v61, v68
	v_mov_b32_e32 v62, v68
	v_mov_b32_e32 v63, v68
	v_mov_b32_e32 v56, v68
	v_mov_b32_e32 v57, v68
	v_mov_b32_e32 v58, v68
	v_mov_b32_e32 v59, v68
	v_mov_b32_e32 v52, v68
	v_mov_b32_e32 v53, v68
	v_mov_b32_e32 v54, v68
	v_mov_b32_e32 v55, v68
	v_mov_b32_e32 v48, v68
	v_mov_b32_e32 v49, v68
	v_mov_b32_e32 v50, v68
	v_mov_b32_e32 v51, v68
	v_mov_b32_e32 v44, v68
	v_mov_b32_e32 v45, v68
	v_mov_b32_e32 v46, v68
	v_mov_b32_e32 v47, v68
	v_mov_b32_e32 v40, v68
	v_mov_b32_e32 v41, v68
	v_mov_b32_e32 v42, v68
	v_mov_b32_e32 v43, v68
	v_mov_b32_e32 v36, v68
	v_mov_b32_e32 v37, v68
	v_mov_b32_e32 v38, v68
	v_mov_b32_e32 v39, v68
	v_mov_b32_e32 v32, v68
	v_mov_b32_e32 v33, v68
	v_mov_b32_e32 v34, v68
	v_mov_b32_e32 v35, v68
	v_mov_b32_e32 v28, v68
	v_mov_b32_e32 v29, v68
	v_mov_b32_e32 v30, v68
	v_mov_b32_e32 v31, v68
	v_mov_b32_e32 v24, v68
	v_mov_b32_e32 v25, v68
	v_mov_b32_e32 v26, v68
	v_mov_b32_e32 v27, v68
	v_mov_b32_e32 v20, v68
	v_mov_b32_e32 v21, v68
	v_mov_b32_e32 v22, v68
	v_mov_b32_e32 v23, v68
	v_mov_b32_e32 v16, v68
	v_mov_b32_e32 v17, v68
	v_mov_b32_e32 v18, v68
	v_mov_b32_e32 v19, v68
	v_mov_b32_e32 v12, v68
	v_mov_b32_e32 v13, v68
	v_mov_b32_e32 v14, v68
	v_mov_b32_e32 v15, v68
	v_mov_b32_e32 v8, v68
	v_mov_b32_e32 v9, v68
	v_mov_b32_e32 v10, v68
	v_mov_b32_e32 v11, v68
	s_waitcnt lgkmcnt(0)
	s_barrier
	v_mov_b32_e32 v176, s1
	v_lshlrev_b32_e32 v176, 23, v176
	v_add_lshl_u32 v176, v176, v126, 1
	v_mov_b32_e32 v177, 0
	v_lshl_add_u64 v[176:177], s[48:49], 0, v[176:177]
	v_lshl_add_u64 v[178:179], v[112:113], 1, v[176:177]
	v_lshl_add_u64 v[180:181], v[116:117], 1, v[176:177]
	global_load_dwordx2 v[182:183], v[178:179], off
	global_load_dwordx2 v[186:187], v[178:179], off offset:32
	global_load_dwordx2 v[188:189], v[178:179], off offset:64
	global_load_dwordx2 v[190:191], v[178:179], off offset:96
	global_load_dwordx2 v[192:193], v[178:179], off offset:128
	global_load_dwordx2 v[194:195], v[178:179], off offset:160
	global_load_dwordx2 v[196:197], v[178:179], off offset:192
	global_load_dwordx2 v[198:199], v[178:179], off offset:224
	global_load_dwordx2 v[200:201], v[178:179], off offset:256
	global_load_dwordx2 v[232:233], v[178:179], off offset:288
	global_load_dwordx2 v[234:235], v[178:179], off offset:320
	global_load_dwordx2 v[236:237], v[178:179], off offset:352
	global_load_dwordx2 v[238:239], v[178:179], off offset:384
	global_load_dwordx2 v[240:241], v[178:179], off offset:416
	global_load_dwordx2 v[242:243], v[178:179], off offset:448
	global_load_dwordx2 v[244:245], v[180:181], off
.LBB0_1258:
	v_add_u32_e32 v0, s4, v128
	v_add_u32_e32 v145, s4, v3
	v_add_u32_e32 v72, 0x10100, v0
	ds_read_b128 v[76:79], v145 offset:480
	ds_read_b128 v[80:83], v145 offset:448
	ds_read_b128 v[146:149], v72
	ds_read_b128 v[108:111], v145 offset:224
	ds_read_b128 v[72:75], v145 offset:192
	ds_read_b128 v[84:87], v145 offset:416
	ds_read_b128 v[88:91], v145 offset:384
	ds_read_b128 v[92:95], v145 offset:352
	ds_read_b128 v[96:99], v145 offset:320
	ds_read_b128 v[100:103], v145 offset:288
	ds_read_b128 v[104:107], v145 offset:256
	s_waitcnt lgkmcnt(7)
	v_mfma_f32_16x16x32_bf16 v[150:153], v[108:111], v[146:149], v[36:39]
	ds_read_b128 v[158:161], v145 offset:96
	ds_read_b128 v[162:165], v145 offset:64
	s_nop 0
	ds_read_b128 v[36:39], v145 offset:160
	s_waitcnt lgkmcnt(9)
	v_mfma_f32_16x16x32_bf16 v[154:157], v[72:75], v[146:149], v[32:35]
	ds_read_b128 v[166:169], v145 offset:32
	ds_read_b128 v[170:173], v145
	v_add_u32_e32 v174, 0x10140, v0
	ds_read_b128 v[32:35], v145 offset:128
	v_mfma_f32_16x16x32_bf16 v[68:71], v[76:79], v[146:149], v[68:71]
	s_add_i32 s3, s3, 4
	s_addk_i32 s4, 0x100
	s_cmp_gt_u32 s3, 59
	v_mfma_f32_16x16x32_bf16 v[64:67], v[80:83], v[146:149], v[64:67]
	s_waitcnt lgkmcnt(11)
	v_mfma_f32_16x16x32_bf16 v[60:63], v[84:87], v[146:149], v[60:63]
	s_waitcnt lgkmcnt(10)
	v_mfma_f32_16x16x32_bf16 v[56:59], v[88:91], v[146:149], v[56:59]
	s_waitcnt lgkmcnt(9)
	v_mfma_f32_16x16x32_bf16 v[52:55], v[92:95], v[146:149], v[52:55]
	s_waitcnt lgkmcnt(8)
	v_mfma_f32_16x16x32_bf16 v[48:51], v[96:99], v[146:149], v[48:51]
	s_waitcnt lgkmcnt(7)
	v_mfma_f32_16x16x32_bf16 v[44:47], v[100:103], v[146:149], v[44:47]
	s_waitcnt lgkmcnt(6)
	v_mfma_f32_16x16x32_bf16 v[40:43], v[104:107], v[146:149], v[40:43]
	s_waitcnt lgkmcnt(3)
	v_mfma_f32_16x16x32_bf16 v[28:31], v[36:39], v[146:149], v[28:31]
	s_waitcnt lgkmcnt(0)
	v_mfma_f32_16x16x32_bf16 v[24:27], v[32:35], v[146:149], v[24:27]
	v_mfma_f32_16x16x32_bf16 v[20:23], v[158:161], v[146:149], v[20:23]
	v_mfma_f32_16x16x32_bf16 v[16:19], v[162:165], v[146:149], v[16:19]
	v_mfma_f32_16x16x32_bf16 v[166:169], v[166:169], v[146:149], v[12:15]
	s_nop 2
	ds_read_b128 v[12:15], v145 offset:544
	v_mfma_f32_16x16x32_bf16 v[8:11], v[170:173], v[146:149], v[8:11]
	ds_read_b128 v[146:149], v174
	ds_read_b128 v[170:173], v145 offset:512
	v_add_u32_e32 v174, 0x10180, v0
	s_waitcnt lgkmcnt(1)
	v_mfma_f32_16x16x32_bf16 v[158:161], v[158:161], v[146:149], v[166:169]
	v_add_u32_e32 v0, 0x101c0, v0
	s_nop 1
	ds_read_b128 v[166:169], v145 offset:608
	v_mfma_f32_16x16x32_bf16 v[8:11], v[162:165], v[146:149], v[8:11]
	ds_read_b128 v[162:165], v145 offset:576
	v_mfma_f32_16x16x32_bf16 v[68:71], v[12:15], v[146:149], v[68:71]
	s_waitcnt lgkmcnt(2)
; #define LAS __attribute__((address_space(3)))
; __device__ __forceinline__ unsigned pk2(float lo, float hi) { const f32v2_t f = {lo, hi}; const bf16v2_t b = __builtin_convertvector(f, bf16v2_t); return __builtin_bit_cast(unsigned, b); }
; __device__ __forceinline__ float bflo(unsigned u) { return __uint_as_float(u << 16); }
; __device__ __forceinline__ float bfhi(unsigned u) { return __uint_as_float(u & 0xFFFF0000u); }
; #define MFMA16(a, b, c) __builtin_amdgcn_mfma_f32_16x16x32_bf16((a), (b), (c), 0, 0, 0)
; template <int L>
; __device__ NOINL void hyena_item(const LAS Params* lp, int l, int c, LAS unsigned char* lds) {
;     ...
;         for (int sb = 0; sb < NS; sb += 4) {
;             bf16x8 Bf[4];
; #pragma unroll
;             for (int u = 0; u < 4; ++u) Bf[u] = *(const LAS bf16x8*)(lds + UOFF + fr * USB + (sb + u) * 64 + fq * 16);
;             bf16x8 Af[NTB + 6];
; #pragma unroll
;             for (int k = 0; k < NTB + 6; ++k) Af[k] = *(const LAS bf16x8*)(lds + abase + sb * 64 + k * 32);
; #pragma unroll
;             for (int a = 0; a < NTB; ++a)
; #pragma unroll
;                 for (int u = 0; u < 4; ++u) acc[a] = MFMA16(Af[NTB - 1 - a + 2 * u], Bf[u], acc[a]);
;         }
;         __syncthreads();
;         const bf16_t* gT = hT + ((size_t)((order + 1) * 256 + c) * NB + fr) * L;
; #pragma unroll
;         for (int a = 0; a < NTB; ++a) {
;             const int t = 16 * (w * NTB + a) + 4 * fq;
;             const u32x2 gv = *(const u32x2*)(gT + t);
;             LAS u32x2* up = (LAS u32x2*)(lds + UOFF + fr * USB + t * 2);
;             const u32x2 uv = *up;
;             const float bias = order == 0 ? bias0 : bias1;
;             const float r0 = bflo(gv.x) * (acc[a][0] + bflo(uv.x) * bias), r1 = bfhi(gv.x) * (acc[a][1] + bfhi(uv.x) * bias);
;             const float r2 = bflo(gv.y) * (acc[a][2] + bflo(uv.y) * bias), r3 = bfhi(gv.y) * (acc[a][3] + bfhi(uv.y) * bias);
;             u32x2 pk; pk.x = pk2(r0, r1); pk.y = pk2(r2, r3);
;             if (order == 0) *up = pk;
	v_mfma_f32_16x16x32_bf16 v[64:67], v[170:173], v[146:149], v[64:67]
	v_mfma_f32_16x16x32_bf16 v[60:63], v[76:79], v[146:149], v[60:63]
	v_mfma_f32_16x16x32_bf16 v[56:59], v[80:83], v[146:149], v[56:59]
	v_mfma_f32_16x16x32_bf16 v[52:55], v[84:87], v[146:149], v[52:55]
	v_mfma_f32_16x16x32_bf16 v[48:51], v[88:91], v[146:149], v[48:51]
	v_mfma_f32_16x16x32_bf16 v[44:47], v[92:95], v[146:149], v[44:47]
	v_mfma_f32_16x16x32_bf16 v[40:43], v[96:99], v[146:149], v[40:43]
	v_mfma_f32_16x16x32_bf16 v[150:153], v[100:103], v[146:149], v[150:153]
	v_mfma_f32_16x16x32_bf16 v[154:157], v[104:107], v[146:149], v[154:157]
	v_mfma_f32_16x16x32_bf16 v[28:31], v[108:111], v[146:149], v[28:31]
	v_mfma_f32_16x16x32_bf16 v[24:27], v[72:75], v[146:149], v[24:27]
	v_mfma_f32_16x16x32_bf16 v[20:23], v[36:39], v[146:149], v[20:23]
	v_mfma_f32_16x16x32_bf16 v[16:19], v[32:35], v[146:149], v[16:19]
	ds_read_b128 v[146:149], v174
	s_waitcnt lgkmcnt(0)
	v_mfma_f32_16x16x32_bf16 v[68:71], v[166:169], v[146:149], v[68:71]
	v_mfma_f32_16x16x32_bf16 v[64:67], v[162:165], v[146:149], v[64:67]
	v_mfma_f32_16x16x32_bf16 v[60:63], v[12:15], v[146:149], v[60:63]
	v_mfma_f32_16x16x32_bf16 v[56:59], v[170:173], v[146:149], v[56:59]
	v_mfma_f32_16x16x32_bf16 v[52:55], v[76:79], v[146:149], v[52:55]
	v_mfma_f32_16x16x32_bf16 v[48:51], v[80:83], v[146:149], v[48:51]
	v_mfma_f32_16x16x32_bf16 v[44:47], v[84:87], v[146:149], v[44:47]
	v_mfma_f32_16x16x32_bf16 v[40:43], v[88:91], v[146:149], v[40:43]
	v_mfma_f32_16x16x32_bf16 v[150:153], v[92:95], v[146:149], v[150:153]
	v_mfma_f32_16x16x32_bf16 v[154:157], v[96:99], v[146:149], v[154:157]
	v_mfma_f32_16x16x32_bf16 v[28:31], v[100:103], v[146:149], v[28:31]
	v_mfma_f32_16x16x32_bf16 v[24:27], v[104:107], v[146:149], v[24:27]
	v_mfma_f32_16x16x32_bf16 v[20:23], v[108:111], v[146:149], v[20:23]
	v_mfma_f32_16x16x32_bf16 v[16:19], v[72:75], v[146:149], v[16:19]
	v_mfma_f32_16x16x32_bf16 v[158:161], v[36:39], v[146:149], v[158:161]
	ds_read_b128 v[36:39], v145 offset:672
	v_mfma_f32_16x16x32_bf16 v[8:11], v[32:35], v[146:149], v[8:11]
	ds_read_b128 v[146:149], v0
	ds_read_b128 v[32:35], v145 offset:640
	s_waitcnt lgkmcnt(1)
	v_mfma_f32_16x16x32_bf16 v[68:71], v[36:39], v[146:149], v[68:71]
	s_waitcnt lgkmcnt(0)
	v_mfma_f32_16x16x32_bf16 v[64:67], v[32:35], v[146:149], v[64:67]
	v_mfma_f32_16x16x32_bf16 v[60:63], v[166:169], v[146:149], v[60:63]
	v_mfma_f32_16x16x32_bf16 v[56:59], v[162:165], v[146:149], v[56:59]
	v_mfma_f32_16x16x32_bf16 v[52:55], v[12:15], v[146:149], v[52:55]
	v_mfma_f32_16x16x32_bf16 v[48:51], v[170:173], v[146:149], v[48:51]
	v_mfma_f32_16x16x32_bf16 v[44:47], v[76:79], v[146:149], v[44:47]
	v_mfma_f32_16x16x32_bf16 v[40:43], v[80:83], v[146:149], v[40:43]
	v_mfma_f32_16x16x32_bf16 v[36:39], v[84:87], v[146:149], v[150:153]
	v_mfma_f32_16x16x32_bf16 v[32:35], v[88:91], v[146:149], v[154:157]
	v_mfma_f32_16x16x32_bf16 v[28:31], v[92:95], v[146:149], v[28:31]
	v_mfma_f32_16x16x32_bf16 v[24:27], v[96:99], v[146:149], v[24:27]
	v_mfma_f32_16x16x32_bf16 v[20:23], v[100:103], v[146:149], v[20:23]
	v_mfma_f32_16x16x32_bf16 v[16:19], v[104:107], v[146:149], v[16:19]
	v_mfma_f32_16x16x32_bf16 v[12:15], v[108:111], v[146:149], v[158:161]
	v_mfma_f32_16x16x32_bf16 v[8:11], v[72:75], v[146:149], v[8:11]
	s_cbranch_scc0 .LBB0_1258
	s_barrier
	v_add_u32_e32 v0, v124, v125
	ds_read_b64 v[76:77], v0
	ds_read_b64 v[78:79], v130
	ds_read_b64 v[80:81], v131
	ds_read_b64 v[82:83], v132
	ds_read_b64 v[84:85], v133
	ds_read_b64 v[86:87], v134
	ds_read_b64 v[88:89], v135
	ds_read_b64 v[90:91], v136
	ds_read_b64 v[92:93], v137
	ds_read_b64 v[94:95], v138
	ds_read_b64 v[96:97], v139
	ds_read_b64 v[98:99], v140
	ds_read_b64 v[100:101], v141
	ds_read_b64 v[102:103], v142
	ds_read_b64 v[104:105], v143
	ds_read_b64 v[106:107], v144
	v_cndmask_b32_e64 v72, v123, v122, s[46:47]
	s_nop 0
	v_mov_b32_e32 v73, v72
	s_waitcnt vmcnt(0)
	s_waitcnt lgkmcnt(14)
	v_lshlrev_b32_e32 v108, 16, v76
	v_and_b32_e32 v109, 0xffff0000, v76
	v_lshlrev_b32_e32 v110, 16, v77
	v_and_b32_e32 v111, 0xffff0000, v77
	v_pk_fma_f32 v[68:69], v[72:73], v[108:109], v[68:69]
	v_pk_fma_f32 v[70:71], v[72:73], v[110:111], v[70:71]
	v_lshlrev_b32_e32 v146, 16, v182
	v_and_b32_e32 v147, 0xffff0000, v182
	v_lshlrev_b32_e32 v148, 16, v183
	v_and_b32_e32 v149, 0xffff0000, v183
	v_pk_mul_f32 v[68:69], v[68:69], v[146:147]
	v_pk_mul_f32 v[70:71], v[70:71], v[148:149]
	v_cvt_pk_bf16_f32 v68, v68, v69
	v_cvt_pk_bf16_f32 v69, v70, v71
	s_waitcnt lgkmcnt(14)
	v_lshlrev_b32_e32 v108, 16, v78
	v_and_b32_e32 v109, 0xffff0000, v78
	v_lshlrev_b32_e32 v110, 16, v79
	v_and_b32_e32 v111, 0xffff0000, v79
	v_pk_fma_f32 v[64:65], v[72:73], v[108:109], v[64:65]
	v_pk_fma_f32 v[66:67], v[72:73], v[110:111], v[66:67]
	v_lshlrev_b32_e32 v146, 16, v186
	v_and_b32_e32 v147, 0xffff0000, v186
	v_lshlrev_b32_e32 v148, 16, v187
	v_and_b32_e32 v149, 0xffff0000, v187
	v_pk_mul_f32 v[64:65], v[64:65], v[146:147]
	v_pk_mul_f32 v[66:67], v[66:67], v[148:149]
	v_cvt_pk_bf16_f32 v64, v64, v65
	v_cvt_pk_bf16_f32 v65, v66, v67
	s_waitcnt lgkmcnt(13)
	v_lshlrev_b32_e32 v108, 16, v80
	v_and_b32_e32 v109, 0xffff0000, v80
	v_lshlrev_b32_e32 v110, 16, v81
	v_and_b32_e32 v111, 0xffff0000, v81
	v_pk_fma_f32 v[60:61], v[72:73], v[108:109], v[60:61]
	v_pk_fma_f32 v[62:63], v[72:73], v[110:111], v[62:63]
	v_lshlrev_b32_e32 v146, 16, v188
	v_and_b32_e32 v147, 0xffff0000, v188
	v_lshlrev_b32_e32 v148, 16, v189
	v_and_b32_e32 v149, 0xffff0000, v189
	v_pk_mul_f32 v[60:61], v[60:61], v[146:147]
	v_pk_mul_f32 v[62:63], v[62:63], v[148:149]
	v_cvt_pk_bf16_f32 v60, v60, v61
	v_cvt_pk_bf16_f32 v61, v62, v63
	s_waitcnt lgkmcnt(12)
; #define LAS __attribute__((address_space(3)))
; __device__ __forceinline__ unsigned pk2(float lo, float hi) { const f32v2_t f = {lo, hi}; const bf16v2_t b = __builtin_convertvector(f, bf16v2_t); return __builtin_bit_cast(unsigned, b); }
; __device__ __forceinline__ float bflo(unsigned u) { return __uint_as_float(u << 16); }
; __device__ __forceinline__ float bfhi(unsigned u) { return __uint_as_float(u & 0xFFFF0000u); }
; template <int L>
; __device__ NOINL void hyena_item(const LAS Params* lp, int l, int c, LAS unsigned char* lds) {
;     ...
;         for (int a = 0; a < NTB; ++a) {
;             const int t = 16 * (w * NTB + a) + 4 * fq;
;             const u32x2 gv = *(const u32x2*)(gT + t);
;             LAS u32x2* up = (LAS u32x2*)(lds + UOFF + fr * USB + t * 2);
;             const u32x2 uv = *up;
;             const float bias = order == 0 ? bias0 : bias1;
;             const float r0 = bflo(gv.x) * (acc[a][0] + bflo(uv.x) * bias), r1 = bfhi(gv.x) * (acc[a][1] + bfhi(uv.x) * bias);
;             const float r2 = bflo(gv.y) * (acc[a][2] + bflo(uv.y) * bias), r3 = bfhi(gv.y) * (acc[a][3] + bfhi(uv.y) * bias);
;             u32x2 pk; pk.x = pk2(r0, r1); pk.y = pk2(r2, r3);
;             if (order == 0) *up = pk;
	v_lshlrev_b32_e32 v108, 16, v82
	v_and_b32_e32 v109, 0xffff0000, v82
	v_lshlrev_b32_e32 v110, 16, v83
	v_and_b32_e32 v111, 0xffff0000, v83
	v_pk_fma_f32 v[56:57], v[72:73], v[108:109], v[56:57]
	v_pk_fma_f32 v[58:59], v[72:73], v[110:111], v[58:59]
	v_lshlrev_b32_e32 v146, 16, v190
	v_and_b32_e32 v147, 0xffff0000, v190
	v_lshlrev_b32_e32 v148, 16, v191
	v_and_b32_e32 v149, 0xffff0000, v191
	v_pk_mul_f32 v[56:57], v[56:57], v[146:147]
	v_pk_mul_f32 v[58:59], v[58:59], v[148:149]
	v_cvt_pk_bf16_f32 v56, v56, v57
	v_cvt_pk_bf16_f32 v57, v58, v59
	s_waitcnt lgkmcnt(11)
	v_lshlrev_b32_e32 v108, 16, v84
	v_and_b32_e32 v109, 0xffff0000, v84
	v_lshlrev_b32_e32 v110, 16, v85
	v_and_b32_e32 v111, 0xffff0000, v85
	v_pk_fma_f32 v[52:53], v[72:73], v[108:109], v[52:53]
	v_pk_fma_f32 v[54:55], v[72:73], v[110:111], v[54:55]
	v_lshlrev_b32_e32 v146, 16, v192
	v_and_b32_e32 v147, 0xffff0000, v192
	v_lshlrev_b32_e32 v148, 16, v193
	v_and_b32_e32 v149, 0xffff0000, v193
	v_pk_mul_f32 v[52:53], v[52:53], v[146:147]
	v_pk_mul_f32 v[54:55], v[54:55], v[148:149]
	v_cvt_pk_bf16_f32 v52, v52, v53
	v_cvt_pk_bf16_f32 v53, v54, v55
	s_waitcnt lgkmcnt(10)
	v_lshlrev_b32_e32 v108, 16, v86
	v_and_b32_e32 v109, 0xffff0000, v86
	v_lshlrev_b32_e32 v110, 16, v87
	v_and_b32_e32 v111, 0xffff0000, v87
	v_pk_fma_f32 v[48:49], v[72:73], v[108:109], v[48:49]
	v_pk_fma_f32 v[50:51], v[72:73], v[110:111], v[50:51]
	v_lshlrev_b32_e32 v146, 16, v194
	v_and_b32_e32 v147, 0xffff0000, v194
	v_lshlrev_b32_e32 v148, 16, v195
	v_and_b32_e32 v149, 0xffff0000, v195
	v_pk_mul_f32 v[48:49], v[48:49], v[146:147]
	v_pk_mul_f32 v[50:51], v[50:51], v[148:149]
	v_cvt_pk_bf16_f32 v48, v48, v49
	v_cvt_pk_bf16_f32 v49, v50, v51
	s_waitcnt lgkmcnt(9)
	v_lshlrev_b32_e32 v108, 16, v88
	v_and_b32_e32 v109, 0xffff0000, v88
	v_lshlrev_b32_e32 v110, 16, v89
	v_and_b32_e32 v111, 0xffff0000, v89
	v_pk_fma_f32 v[44:45], v[72:73], v[108:109], v[44:45]
	v_pk_fma_f32 v[46:47], v[72:73], v[110:111], v[46:47]
	v_lshlrev_b32_e32 v146, 16, v196
	v_and_b32_e32 v147, 0xffff0000, v196
	v_lshlrev_b32_e32 v148, 16, v197
	v_and_b32_e32 v149, 0xffff0000, v197
	v_pk_mul_f32 v[44:45], v[44:45], v[146:147]
	v_pk_mul_f32 v[46:47], v[46:47], v[148:149]
	v_cvt_pk_bf16_f32 v44, v44, v45
	v_cvt_pk_bf16_f32 v45, v46, v47
	s_waitcnt lgkmcnt(8)
	v_lshlrev_b32_e32 v108, 16, v90
	v_and_b32_e32 v109, 0xffff0000, v90
	v_lshlrev_b32_e32 v110, 16, v91
	v_and_b32_e32 v111, 0xffff0000, v91
	v_pk_fma_f32 v[40:41], v[72:73], v[108:109], v[40:41]
	v_pk_fma_f32 v[42:43], v[72:73], v[110:111], v[42:43]
	v_lshlrev_b32_e32 v146, 16, v198
	v_and_b32_e32 v147, 0xffff0000, v198
	v_lshlrev_b32_e32 v148, 16, v199
	v_and_b32_e32 v149, 0xffff0000, v199
	v_pk_mul_f32 v[40:41], v[40:41], v[146:147]
	v_pk_mul_f32 v[42:43], v[42:43], v[148:149]
	v_cvt_pk_bf16_f32 v40, v40, v41
	v_cvt_pk_bf16_f32 v41, v42, v43
	s_waitcnt lgkmcnt(7)
	v_lshlrev_b32_e32 v108, 16, v92
	v_and_b32_e32 v109, 0xffff0000, v92
	v_lshlrev_b32_e32 v110, 16, v93
	v_and_b32_e32 v111, 0xffff0000, v93
	v_pk_fma_f32 v[36:37], v[72:73], v[108:109], v[36:37]
	v_pk_fma_f32 v[38:39], v[72:73], v[110:111], v[38:39]
	v_lshlrev_b32_e32 v146, 16, v200
	v_and_b32_e32 v147, 0xffff0000, v200
	v_lshlrev_b32_e32 v148, 16, v201
	v_and_b32_e32 v149, 0xffff0000, v201
	v_pk_mul_f32 v[36:37], v[36:37], v[146:147]
	v_pk_mul_f32 v[38:39], v[38:39], v[148:149]
	v_cvt_pk_bf16_f32 v36, v36, v37
	v_cvt_pk_bf16_f32 v37, v38, v39
	s_waitcnt lgkmcnt(6)
	v_lshlrev_b32_e32 v108, 16, v94
	v_and_b32_e32 v109, 0xffff0000, v94
	v_lshlrev_b32_e32 v110, 16, v95
	v_and_b32_e32 v111, 0xffff0000, v95
	v_pk_fma_f32 v[32:33], v[72:73], v[108:109], v[32:33]
	v_pk_fma_f32 v[34:35], v[72:73], v[110:111], v[34:35]
	v_lshlrev_b32_e32 v146, 16, v232
	v_and_b32_e32 v147, 0xffff0000, v232
	v_lshlrev_b32_e32 v148, 16, v233
	v_and_b32_e32 v149, 0xffff0000, v233
	v_pk_mul_f32 v[32:33], v[32:33], v[146:147]
	v_pk_mul_f32 v[34:35], v[34:35], v[148:149]
	v_cvt_pk_bf16_f32 v32, v32, v33
	v_cvt_pk_bf16_f32 v33, v34, v35
	s_waitcnt lgkmcnt(5)
	v_lshlrev_b32_e32 v108, 16, v96
	v_and_b32_e32 v109, 0xffff0000, v96
	v_lshlrev_b32_e32 v110, 16, v97
	v_and_b32_e32 v111, 0xffff0000, v97
	v_pk_fma_f32 v[28:29], v[72:73], v[108:109], v[28:29]
	v_pk_fma_f32 v[30:31], v[72:73], v[110:111], v[30:31]
	v_lshlrev_b32_e32 v146, 16, v234
	v_and_b32_e32 v147, 0xffff0000, v234
	v_lshlrev_b32_e32 v148, 16, v235
	v_and_b32_e32 v149, 0xffff0000, v235
	v_pk_mul_f32 v[28:29], v[28:29], v[146:147]
	v_pk_mul_f32 v[30:31], v[30:31], v[148:149]
	v_cvt_pk_bf16_f32 v28, v28, v29
	v_cvt_pk_bf16_f32 v29, v30, v31
	s_waitcnt lgkmcnt(4)
; #define LAS __attribute__((address_space(3)))
; __device__ __forceinline__ unsigned pk2(float lo, float hi) { const f32v2_t f = {lo, hi}; const bf16v2_t b = __builtin_convertvector(f, bf16v2_t); return __builtin_bit_cast(unsigned, b); }
; __device__ __forceinline__ float bflo(unsigned u) { return __uint_as_float(u << 16); }
; __device__ __forceinline__ float bfhi(unsigned u) { return __uint_as_float(u & 0xFFFF0000u); }
; template <int L>
; __device__ NOINL void hyena_item(const LAS Params* lp, int l, int c, LAS unsigned char* lds) {
;     ...
;         const bf16_t* gT = hT + ((size_t)((order + 1) * 256 + c) * NB + fr) * L;
; #pragma unroll
;         for (int a = 0; a < NTB; ++a) {
;             const int t = 16 * (w * NTB + a) + 4 * fq;
;             const u32x2 gv = *(const u32x2*)(gT + t);
;             LAS u32x2* up = (LAS u32x2*)(lds + UOFF + fr * USB + t * 2);
;             const u32x2 uv = *up;
;             const float bias = order == 0 ? bias0 : bias1;
;             const float r0 = bflo(gv.x) * (acc[a][0] + bflo(uv.x) * bias), r1 = bfhi(gv.x) * (acc[a][1] + bfhi(uv.x) * bias);
;             const float r2 = bflo(gv.y) * (acc[a][2] + bflo(uv.y) * bias), r3 = bfhi(gv.y) * (acc[a][3] + bfhi(uv.y) * bias);
;             u32x2 pk; pk.x = pk2(r0, r1); pk.y = pk2(r2, r3);
;             if (order == 0) *up = pk;
;             else *(u32x2*)(hO + ((size_t)c * NB + fr) * L + t) = pk;
;         }
	v_lshlrev_b32_e32 v108, 16, v98
	v_and_b32_e32 v109, 0xffff0000, v98
	v_lshlrev_b32_e32 v110, 16, v99
	v_and_b32_e32 v111, 0xffff0000, v99
	v_pk_fma_f32 v[24:25], v[72:73], v[108:109], v[24:25]
	v_pk_fma_f32 v[26:27], v[72:73], v[110:111], v[26:27]
	v_lshlrev_b32_e32 v146, 16, v236
	v_and_b32_e32 v147, 0xffff0000, v236
	v_lshlrev_b32_e32 v148, 16, v237
	v_and_b32_e32 v149, 0xffff0000, v237
	v_pk_mul_f32 v[24:25], v[24:25], v[146:147]
	v_pk_mul_f32 v[26:27], v[26:27], v[148:149]
	v_cvt_pk_bf16_f32 v24, v24, v25
	v_cvt_pk_bf16_f32 v25, v26, v27
	s_waitcnt lgkmcnt(3)
	v_lshlrev_b32_e32 v108, 16, v100
	v_and_b32_e32 v109, 0xffff0000, v100
	v_lshlrev_b32_e32 v110, 16, v101
	v_and_b32_e32 v111, 0xffff0000, v101
	v_pk_fma_f32 v[20:21], v[72:73], v[108:109], v[20:21]
	v_pk_fma_f32 v[22:23], v[72:73], v[110:111], v[22:23]
	v_lshlrev_b32_e32 v146, 16, v238
	v_and_b32_e32 v147, 0xffff0000, v238
	v_lshlrev_b32_e32 v148, 16, v239
	v_and_b32_e32 v149, 0xffff0000, v239
	v_pk_mul_f32 v[20:21], v[20:21], v[146:147]
	v_pk_mul_f32 v[22:23], v[22:23], v[148:149]
	v_cvt_pk_bf16_f32 v20, v20, v21
	v_cvt_pk_bf16_f32 v21, v22, v23
	s_waitcnt lgkmcnt(2)
	v_lshlrev_b32_e32 v108, 16, v102
	v_and_b32_e32 v109, 0xffff0000, v102
	v_lshlrev_b32_e32 v110, 16, v103
	v_and_b32_e32 v111, 0xffff0000, v103
	v_pk_fma_f32 v[16:17], v[72:73], v[108:109], v[16:17]
	v_pk_fma_f32 v[18:19], v[72:73], v[110:111], v[18:19]
	v_lshlrev_b32_e32 v146, 16, v240
	v_and_b32_e32 v147, 0xffff0000, v240
	v_lshlrev_b32_e32 v148, 16, v241
	v_and_b32_e32 v149, 0xffff0000, v241
	v_pk_mul_f32 v[16:17], v[16:17], v[146:147]
	v_pk_mul_f32 v[18:19], v[18:19], v[148:149]
	v_cvt_pk_bf16_f32 v16, v16, v17
	v_cvt_pk_bf16_f32 v17, v18, v19
	s_waitcnt lgkmcnt(1)
	v_lshlrev_b32_e32 v108, 16, v104
	v_and_b32_e32 v109, 0xffff0000, v104
	v_lshlrev_b32_e32 v110, 16, v105
	v_and_b32_e32 v111, 0xffff0000, v105
	v_pk_fma_f32 v[12:13], v[72:73], v[108:109], v[12:13]
	v_pk_fma_f32 v[14:15], v[72:73], v[110:111], v[14:15]
	v_lshlrev_b32_e32 v146, 16, v242
	v_and_b32_e32 v147, 0xffff0000, v242
	v_lshlrev_b32_e32 v148, 16, v243
	v_and_b32_e32 v149, 0xffff0000, v243
	v_pk_mul_f32 v[12:13], v[12:13], v[146:147]
	v_pk_mul_f32 v[14:15], v[14:15], v[148:149]
	v_cvt_pk_bf16_f32 v12, v12, v13
	v_cvt_pk_bf16_f32 v13, v14, v15
	s_waitcnt lgkmcnt(0)
	v_lshlrev_b32_e32 v108, 16, v106
	v_and_b32_e32 v109, 0xffff0000, v106
	v_lshlrev_b32_e32 v110, 16, v107
	v_and_b32_e32 v111, 0xffff0000, v107
	v_pk_fma_f32 v[8:9], v[72:73], v[108:109], v[8:9]
	v_pk_fma_f32 v[10:11], v[72:73], v[110:111], v[10:11]
	v_lshlrev_b32_e32 v146, 16, v244
	v_and_b32_e32 v147, 0xffff0000, v244
	v_lshlrev_b32_e32 v148, 16, v245
	v_and_b32_e32 v149, 0xffff0000, v245
	v_pk_mul_f32 v[8:9], v[8:9], v[146:147]
	v_pk_mul_f32 v[10:11], v[10:11], v[148:149]
	v_cvt_pk_bf16_f32 v8, v8, v9
	v_cvt_pk_bf16_f32 v9, v10, v11
	s_and_b64 vcc, exec, s[52:53]
	s_cbranch_vccz .Lmy_hyep_lds
	global_store_dwordx2 v[114:115], v[68:69], off
	global_store_dwordx2 v[114:115], v[64:65], off offset:32
	global_store_dwordx2 v[114:115], v[60:61], off offset:64
	global_store_dwordx2 v[114:115], v[56:57], off offset:96
	global_store_dwordx2 v[114:115], v[52:53], off offset:128
	global_store_dwordx2 v[114:115], v[48:49], off offset:160
	global_store_dwordx2 v[114:115], v[44:45], off offset:192
	global_store_dwordx2 v[114:115], v[40:41], off offset:224
	global_store_dwordx2 v[114:115], v[36:37], off offset:256
	global_store_dwordx2 v[114:115], v[32:33], off offset:288
	global_store_dwordx2 v[114:115], v[28:29], off offset:320
	global_store_dwordx2 v[114:115], v[24:25], off offset:352
	global_store_dwordx2 v[114:115], v[20:21], off offset:384
	global_store_dwordx2 v[114:115], v[16:17], off offset:416
	global_store_dwordx2 v[114:115], v[12:13], off offset:448
	global_store_dwordx2 v[118:119], v[8:9], off
	s_branch .LBB0_1233
.Lmy_hyep_lds:
	ds_write_b64 v0, v[68:69]
	ds_write_b64 v130, v[64:65]
	ds_write_b64 v131, v[60:61]
	ds_write_b64 v132, v[56:57]
	ds_write_b64 v133, v[52:53]
	ds_write_b64 v134, v[48:49]
	ds_write_b64 v135, v[44:45]
	ds_write_b64 v136, v[40:41]
	ds_write_b64 v137, v[36:37]
	ds_write_b64 v138, v[32:33]
	ds_write_b64 v139, v[28:29]
	ds_write_b64 v140, v[24:25]
	ds_write_b64 v141, v[20:21]
	ds_write_b64 v142, v[16:17]
	ds_write_b64 v143, v[12:13]
	ds_write_b64 v144, v[8:9]
	s_branch .LBB0_1233
